# chunk code entry barrier removed (the first stage only reads data published before the compiler's own barrier)
# speedup vs baseline: 1.0009x; 1.0009x over previous
; __device__ __forceinline__ void dn_task(const Params& p, int l, int task, char* smem) {
;     ...
;     {
;       const int did = tid >> 2, pp = did >> 2, wh = did & 3, part = tid & 3;
;       const float* xr = (wh == 0) ? (ks + (2 * pp + 1) * 68) : (wh == 1) ? (qs + (2 * pp) * 68) : (qs + (2 * pp + 1) * 68);
;       const float* yr = (wh == 3) ? (ks + (2 * pp + 1) * 68) : (ks + (2 * pp) * 68);
;       float sdot = 0.f;
; #pragma unroll
;       for (int i = 0; i < 16; ++i) sdot += xr[part * 16 + i] * yr[part * 16 + i];
;       sdot = quad_sum(sdot);
;       if (part == 0) dots[did] = sdot;
;     }
.LBB0_207:
	v_and_b32_e32 v221, 63, v172
	v_and_b32_e32 v222, 15, v221
	v_lshrrev_b32_e32 v223, 4, v221
	v_mul_u32_u24_e32 v224, 0x110, v222
	v_lshl_add_u32 v224, v223, 6, v224
	v_mul_u32_u24_e32 v225, 0x240, v223
	v_lshl_add_u32 v225, v222, 2, v225
	v_readfirstlane_b32 s60, v172
	s_nop 3
	s_lshr_b32 s60, s60, 6
	v_lshrrev_b32_e32 v244, 3, v172
	v_lshlrev_b32_e32 v244, 2, v244
	v_sub_u32_e32 v248, v167, v244
	s_and_b32 s61, s60, 1
	s_lshl_b32 s61, s61, 6
	v_mul_u32_u24_e32 v244, 0x840, v223
	v_lshl_add_u32 v244, v222, 2, v244
	s_add_i32 s61, s61, 0x11600
	v_add_u32_e32 v244, s61, v244
	ds_read_b32 v10, v244 offset:0
	ds_read_b32 v11, v244 offset:132
	ds_read_b32 v12, v244 offset:264
	ds_read_b32 v13, v244 offset:396
	ds_read_b32 v14, v244 offset:528
	ds_read_b32 v15, v244 offset:660
	ds_read_b32 v16, v244 offset:792
	ds_read_b32 v17, v244 offset:924
	ds_read_b32 v18, v244 offset:1056
	ds_read_b32 v19, v244 offset:1188
	ds_read_b32 v20, v244 offset:1320
	ds_read_b32 v21, v244 offset:1452
	ds_read_b32 v22, v244 offset:1584
	ds_read_b32 v23, v244 offset:1716
	ds_read_b32 v24, v244 offset:1848
	ds_read_b32 v25, v244 offset:1980
	s_lshr_b32 s61, s60, 1
	s_mul_i32 s70, s61, 0x1100
	v_add_u32_e32 v246, s70, v224
	ds_read_b128 v[66:69], v246 offset:8704
	ds_read_b128 v[70:73], v246 offset:8720
	ds_read_b128 v[74:77], v246 offset:8736
	ds_read_b128 v[78:81], v246 offset:8752
	s_cmp_eq_u32 s60, 3
	s_cbranch_scc1 .Ldc_w3
	s_cmp_eq_u32 s60, 1
	s_cbranch_scc1 .Ldc_k1
	s_waitcnt lgkmcnt(0)
	v_mfma_f32_16x16x4_f32 v[62:65], v66, v10, 0
	v_mfma_f32_16x16x4_f32 v[58:61], v66, v66, 0
	v_mfma_f32_16x16x4_f32 v[62:65], v67, v11, v[62:65]
	v_mfma_f32_16x16x4_f32 v[58:61], v67, v67, v[58:61]
	v_mfma_f32_16x16x4_f32 v[62:65], v68, v12, v[62:65]
	v_mfma_f32_16x16x4_f32 v[58:61], v68, v68, v[58:61]
	v_mfma_f32_16x16x4_f32 v[62:65], v69, v13, v[62:65]
	v_mfma_f32_16x16x4_f32 v[58:61], v69, v69, v[58:61]
	v_mfma_f32_16x16x4_f32 v[62:65], v70, v14, v[62:65]
	v_mfma_f32_16x16x4_f32 v[58:61], v70, v70, v[58:61]
	v_mfma_f32_16x16x4_f32 v[62:65], v71, v15, v[62:65]
	v_mfma_f32_16x16x4_f32 v[58:61], v71, v71, v[58:61]
	v_mfma_f32_16x16x4_f32 v[62:65], v72, v16, v[62:65]
	v_mfma_f32_16x16x4_f32 v[58:61], v72, v72, v[58:61]
	v_mfma_f32_16x16x4_f32 v[62:65], v73, v17, v[62:65]
	v_mfma_f32_16x16x4_f32 v[58:61], v73, v73, v[58:61]
	v_mfma_f32_16x16x4_f32 v[62:65], v74, v18, v[62:65]
	v_mfma_f32_16x16x4_f32 v[58:61], v74, v74, v[58:61]
	v_mfma_f32_16x16x4_f32 v[62:65], v75, v19, v[62:65]
	v_mfma_f32_16x16x4_f32 v[58:61], v75, v75, v[58:61]
	v_mfma_f32_16x16x4_f32 v[62:65], v76, v20, v[62:65]
	v_mfma_f32_16x16x4_f32 v[58:61], v76, v76, v[58:61]
	v_mfma_f32_16x16x4_f32 v[62:65], v77, v21, v[62:65]
	v_mfma_f32_16x16x4_f32 v[58:61], v77, v77, v[58:61]
	v_mfma_f32_16x16x4_f32 v[62:65], v78, v22, v[62:65]
	v_mfma_f32_16x16x4_f32 v[58:61], v78, v78, v[58:61]
	v_mfma_f32_16x16x4_f32 v[62:65], v79, v23, v[62:65]
	v_mfma_f32_16x16x4_f32 v[58:61], v79, v79, v[58:61]
	v_mfma_f32_16x16x4_f32 v[62:65], v80, v24, v[62:65]
	v_mfma_f32_16x16x4_f32 v[58:61], v80, v80, v[58:61]
	v_mfma_f32_16x16x4_f32 v[62:65], v81, v25, v[62:65]
	v_mfma_f32_16x16x4_f32 v[58:61], v81, v81, v[58:61]
	s_branch .Ldc_b1
